# grid barriers: TOP hop removed (each XCD flusher bumps the release word of every XCD, waiters leave at nx*(k+1))
# baseline (speedup 1.0000x reference)
; #define RUN_PHASE(k, fn)                                  \
;   if (ph_lo <= k && k <= ph_hi) {                         \
;     if (k == PROBE_DUP) { fn(p, smem); cg::this_grid().sync(); } \
;     fn(p, smem);                                          \
;     if (k < ph_hi) cg::this_grid().sync();                \
;   }
; __global__ void __launch_bounds__(512) mega(Params p, int ph_lo, int ph_hi) {
;     ...
;   RUN_PHASE(0, phase0)
.Lgbf_census_ok:
	s_mov_b32 s98, s12
	s_cmp_eq_u32 s100, 1
	s_cselect_b32 s98, s13, s98
	s_cmp_eq_u32 s100, 2
	s_cselect_b32 s98, s14, s98
	s_cmp_eq_u32 s100, 3
	s_cselect_b32 s98, s15, s98
	s_cmp_eq_u32 s100, 4
	s_cselect_b32 s98, s16, s98
	s_cmp_eq_u32 s100, 5
	s_cselect_b32 s98, s17, s98
	s_cmp_eq_u32 s100, 6
	s_cselect_b32 s98, s18, s98
	s_cmp_eq_u32 s100, 7
	s_cselect_b32 s98, s19, s98
	s_max_u32 s98, s98, 1
	s_max_u32 s99, s21, 1
	s_add_i32 s1, s0, 0x800
	v_mov_b32_e32 v1, s1
	global_atomic_add v2, v1, v11, s[86:87] sc0
	s_add_i32 s2, s0, 0x1000
	s_waitcnt vmcnt(0)
	v_readfirstlane_b32 s7, v2
	s_cmp_eq_u32 s7, 0
	s_cbranch_scc0 .Lgbf_wait
	buffer_wbl2 sc1
	s_waitcnt vmcnt(0)
	v_mov_b32_e32 v12, 0x1000
	global_atomic_add v12, v11, s[86:87]
	global_atomic_add v12, v11, s[86:87] offset:256
	global_atomic_add v12, v11, s[86:87] offset:512
	global_atomic_add v12, v11, s[86:87] offset:768
	global_atomic_add v12, v11, s[86:87] offset:1024
	global_atomic_add v12, v11, s[86:87] offset:1280
	global_atomic_add v12, v11, s[86:87] offset:1536
	global_atomic_add v12, v11, s[86:87] offset:1792

; #define RUN_PHASE(k, fn)                                  \
;   if (ph_lo <= k && k <= ph_hi) {                         \
;     if (k == PROBE_DUP) { fn(p, smem); cg::this_grid().sync(); } \
;     fn(p, smem);                                          \
;     if (k < ph_hi) cg::this_grid().sync();                \
;   }
; __global__ void __launch_bounds__(512) mega(Params p, int ph_lo, int ph_hi) {
;     ...
;   RUN_PHASE(0, phase0)
.Lgbf_spin:
	global_atomic_add v2, v1, v10, s[86:87] sc0
	s_waitcnt vmcnt(0)
	v_readfirstlane_b32 s7, v2
	s_cmp_ge_u32 s7, s99
	s_cbranch_scc1 .Lgbf_acq
	s_sleep 1
	s_sub_i32 s11, s11, 1
	s_cmp_lg_u32 s11, 0
	s_cbranch_scc1 .Lgbf_spin

; #define RUN_PHASE(k, fn)                                  \
;   if (ph_lo <= k && k <= ph_hi) {                         \
;     if (k == PROBE_DUP) { fn(p, smem); cg::this_grid().sync(); } \
;     fn(p, smem);                                          \
;     if (k < ph_hi) cg::this_grid().sync();                \
;   }
; __global__ void __launch_bounds__(512) mega(Params p, int ph_lo, int ph_hi) {
;     ...
;   RUN_PHASE(0, phase0)
;   RUN_PHASE(1, phase1)
.LBB0_512:
	s_cmp_lt_i32 s91, 2
	s_cbranch_scc1 .LBB0_524
	s_waitcnt vmcnt(0) lgkmcnt(0)
	s_barrier
	v_cmp_eq_u32_e32 vcc, 0, v0
	s_and_saveexec_b64 s[4:5], vcc
	s_cbranch_execz .Lgb0_done
	s_add_u32 s8, s88, 0xb20000
	s_addc_u32 s9, s89, 0
	v_mov_b32_e32 v10, 0
	v_mov_b32_e32 v11, 1
	s_lshl_b32 s0, s100, 8
	s_add_i32 s1, s0, 0x1000
	v_mov_b32_e32 v1, s1
	global_atomic_add v2, v1, v11, s[8:9] sc0
	s_add_i32 s2, s0, 0x2000
	s_mul_i32 s3, s98, 1
	s_mul_i32 s6, s99, 1
	s_waitcnt vmcnt(0)
	v_readfirstlane_b32 s7, v2
	s_add_i32 s7, s7, 1
	s_cmp_eq_u32 s7, s3
	s_cbranch_scc0 .Lgb0_wait
	buffer_wbl2 sc1
	s_waitcnt vmcnt(0)
	v_mov_b32_e32 v12, 0x2000
	global_atomic_add v12, v11, s[8:9]
	global_atomic_add v12, v11, s[8:9] offset:256
	global_atomic_add v12, v11, s[8:9] offset:512
	global_atomic_add v12, v11, s[8:9] offset:768
	global_atomic_add v12, v11, s[8:9] offset:1024
	global_atomic_add v12, v11, s[8:9] offset:1280
	global_atomic_add v12, v11, s[8:9] offset:1536
	global_atomic_add v12, v11, s[8:9] offset:1792

; #define RUN_PHASE(k, fn)                                  \
;   if (ph_lo <= k && k <= ph_hi) {                         \
;     if (k == PROBE_DUP) { fn(p, smem); cg::this_grid().sync(); } \
;     fn(p, smem);                                          \
;     if (k < ph_hi) cg::this_grid().sync();                \
;   }
; __global__ void __launch_bounds__(512) mega(Params p, int ph_lo, int ph_hi) {
;     ...
;   RUN_PHASE(0, phase0)
;   RUN_PHASE(1, phase1)
.Lgb0_spin:
	s_sleep 1
	global_atomic_add v2, v1, v10, s[8:9] sc0
	s_waitcnt vmcnt(0)
	v_readfirstlane_b32 s7, v2
	s_cmp_ge_u32 s7, s6
	s_cbranch_scc1 .Lgb0_acq
	s_sub_i32 s11, s11, 1
	s_cmp_lg_u32 s11, 0
	s_cbranch_scc1 .Lgb0_spin

; #define RUN_PHASE(k, fn)                                  \
;   if (ph_lo <= k && k <= ph_hi) {                         \
;     if (k == PROBE_DUP) { fn(p, smem); cg::this_grid().sync(); } \
;     fn(p, smem);                                          \
;     if (k < ph_hi) cg::this_grid().sync();                \
;   }
; __global__ void __launch_bounds__(512) mega(Params p, int ph_lo, int ph_hi) {
;     ...
;   RUN_PHASE(2, phase2)
.LBB0_596:
	s_cmp_lt_i32 s91, 3
	s_cbranch_scc1 .LBB0_608
	s_waitcnt vmcnt(0) lgkmcnt(0)
	s_barrier
	v_cmp_eq_u32_e32 vcc, 0, v0
	s_and_saveexec_b64 s[4:5], vcc
	s_cbranch_execz .Lgb1_done
	s_add_u32 s8, s88, 0xb20000
	s_addc_u32 s9, s89, 0
	v_mov_b32_e32 v10, 0
	v_mov_b32_e32 v11, 1
	s_lshl_b32 s0, s100, 8
	s_add_i32 s1, s0, 0x1000
	v_mov_b32_e32 v1, s1
	global_atomic_add v2, v1, v11, s[8:9] sc0
	s_add_i32 s2, s0, 0x2000
	s_mul_i32 s3, s98, 2
	s_mul_i32 s6, s99, 2
	s_waitcnt vmcnt(0)
	v_readfirstlane_b32 s7, v2
	s_add_i32 s7, s7, 1
	s_cmp_eq_u32 s7, s3
	s_cbranch_scc0 .Lgb1_wait
	buffer_wbl2 sc1
	s_waitcnt vmcnt(0)
	v_mov_b32_e32 v12, 0x2000
	global_atomic_add v12, v11, s[8:9]
	global_atomic_add v12, v11, s[8:9] offset:256
	global_atomic_add v12, v11, s[8:9] offset:512
	global_atomic_add v12, v11, s[8:9] offset:768
	global_atomic_add v12, v11, s[8:9] offset:1024
	global_atomic_add v12, v11, s[8:9] offset:1280
	global_atomic_add v12, v11, s[8:9] offset:1536
	global_atomic_add v12, v11, s[8:9] offset:1792

; #define RUN_PHASE(k, fn)                                  \
;   if (ph_lo <= k && k <= ph_hi) {                         \
;     if (k == PROBE_DUP) { fn(p, smem); cg::this_grid().sync(); } \
;     fn(p, smem);                                          \
;     if (k < ph_hi) cg::this_grid().sync();                \
;   }
; __global__ void __launch_bounds__(512) mega(Params p, int ph_lo, int ph_hi) {
;     ...
;   RUN_PHASE(3, phase3)
.LBB0_664:
	s_cmp_lt_i32 s91, 4
	s_cbranch_scc1 .LBB0_676
	s_waitcnt vmcnt(0) lgkmcnt(0)
	s_barrier
	v_cmp_eq_u32_e32 vcc, 0, v0
	s_and_saveexec_b64 s[4:5], vcc
	s_cbranch_execz .Lgb2_done
	s_add_u32 s8, s88, 0xb20000
	s_addc_u32 s9, s89, 0
	v_mov_b32_e32 v10, 0
	v_mov_b32_e32 v11, 1
	s_lshl_b32 s0, s100, 8
	s_add_i32 s1, s0, 0x1000
	v_mov_b32_e32 v1, s1
	global_atomic_add v2, v1, v11, s[8:9] sc0
	s_add_i32 s2, s0, 0x2000
	s_mul_i32 s3, s98, 3
	s_mul_i32 s6, s99, 3
	s_waitcnt vmcnt(0)
	v_readfirstlane_b32 s7, v2
	s_add_i32 s7, s7, 1
	s_cmp_eq_u32 s7, s3
	s_cbranch_scc0 .Lgb2_wait
	buffer_wbl2 sc1
	s_waitcnt vmcnt(0)
	v_mov_b32_e32 v12, 0x2000
	global_atomic_add v12, v11, s[8:9]
	global_atomic_add v12, v11, s[8:9] offset:256
	global_atomic_add v12, v11, s[8:9] offset:512
	global_atomic_add v12, v11, s[8:9] offset:768
	global_atomic_add v12, v11, s[8:9] offset:1024
	global_atomic_add v12, v11, s[8:9] offset:1280
	global_atomic_add v12, v11, s[8:9] offset:1536
	global_atomic_add v12, v11, s[8:9] offset:1792

; #define RUN_PHASE(k, fn)                                  \
;   if (ph_lo <= k && k <= ph_hi) {                         \
;     if (k == PROBE_DUP) { fn(p, smem); cg::this_grid().sync(); } \
;     fn(p, smem);                                          \
;     if (k < ph_hi) cg::this_grid().sync();                \
;   }
; __global__ void __launch_bounds__(512) mega(Params p, int ph_lo, int ph_hi) {
;     ...
;   RUN_PHASE(4, phase4)
.LBB0_718:
	s_cmp_lt_i32 s91, 5
	s_cbranch_scc1 .LBB0_730
	s_waitcnt vmcnt(0) lgkmcnt(0)
	s_barrier
	v_cmp_eq_u32_e32 vcc, 0, v0
	s_and_saveexec_b64 s[4:5], vcc
	s_cbranch_execz .Lgb3_done
	s_add_u32 s8, s88, 0xb20000
	s_addc_u32 s9, s89, 0
	v_mov_b32_e32 v10, 0
	v_mov_b32_e32 v11, 1
	s_lshl_b32 s0, s100, 8
	s_add_i32 s1, s0, 0x1000
	v_mov_b32_e32 v1, s1
	global_atomic_add v2, v1, v11, s[8:9] sc0
	s_add_i32 s2, s0, 0x2000
	s_mul_i32 s3, s98, 4
	s_mul_i32 s6, s99, 4
	s_waitcnt vmcnt(0)
	v_readfirstlane_b32 s7, v2
	s_add_i32 s7, s7, 1
	s_cmp_eq_u32 s7, s3
	s_cbranch_scc0 .Lgb3_wait
	buffer_wbl2 sc1
	s_waitcnt vmcnt(0)
	v_mov_b32_e32 v12, 0x2000
	global_atomic_add v12, v11, s[8:9]
	global_atomic_add v12, v11, s[8:9] offset:256
	global_atomic_add v12, v11, s[8:9] offset:512
	global_atomic_add v12, v11, s[8:9] offset:768
	global_atomic_add v12, v11, s[8:9] offset:1024
	global_atomic_add v12, v11, s[8:9] offset:1280
	global_atomic_add v12, v11, s[8:9] offset:1536
	global_atomic_add v12, v11, s[8:9] offset:1792

; #define RUN_PHASE(k, fn)                                  \
;   if (ph_lo <= k && k <= ph_hi) {                         \
;     if (k == PROBE_DUP) { fn(p, smem); cg::this_grid().sync(); } \
;     fn(p, smem);                                          \
;     if (k < ph_hi) cg::this_grid().sync();                \
;   }
; __global__ void __launch_bounds__(512) mega(Params p, int ph_lo, int ph_hi) {
;     ...
;   RUN_PHASE(5, phase5)
.LBB0_770:
	s_cmp_lt_i32 s91, 6
	s_cbranch_scc1 .LBB0_782
	s_waitcnt vmcnt(0) lgkmcnt(0)
	s_barrier
	v_cmp_eq_u32_e32 vcc, 0, v0
	s_and_saveexec_b64 s[4:5], vcc
	s_cbranch_execz .Lgb4_done
	s_add_u32 s8, s88, 0xb20000
	s_addc_u32 s9, s89, 0
	v_mov_b32_e32 v10, 0
	v_mov_b32_e32 v11, 1
	s_lshl_b32 s0, s100, 8
	s_add_i32 s1, s0, 0x1000
	v_mov_b32_e32 v1, s1
	global_atomic_add v2, v1, v11, s[8:9] sc0
	s_add_i32 s2, s0, 0x2000
	s_mul_i32 s3, s98, 5
	s_mul_i32 s6, s99, 5
	s_waitcnt vmcnt(0)
	v_readfirstlane_b32 s7, v2
	s_add_i32 s7, s7, 1
	s_cmp_eq_u32 s7, s3
	s_cbranch_scc0 .Lgb4_wait
	buffer_wbl2 sc1
	s_waitcnt vmcnt(0)
	v_mov_b32_e32 v12, 0x2000
	global_atomic_add v12, v11, s[8:9]
	global_atomic_add v12, v11, s[8:9] offset:256
	global_atomic_add v12, v11, s[8:9] offset:512
	global_atomic_add v12, v11, s[8:9] offset:768
	global_atomic_add v12, v11, s[8:9] offset:1024
	global_atomic_add v12, v11, s[8:9] offset:1280
	global_atomic_add v12, v11, s[8:9] offset:1536
	global_atomic_add v12, v11, s[8:9] offset:1792

; #define RUN_PHASE(k, fn)                                  \
;   if (ph_lo <= k && k <= ph_hi) {                         \
;     if (k == PROBE_DUP) { fn(p, smem); cg::this_grid().sync(); } \
;     fn(p, smem);                                          \
;     if (k < ph_hi) cg::this_grid().sync();                \
;   }
; __global__ void __launch_bounds__(512) mega(Params p, int ph_lo, int ph_hi) {
;     ...
;   RUN_PHASE(6, phase6)
.LBB0_805:
	s_cmp_lt_i32 s91, 7
	s_cbranch_scc1 .LBB0_817
	s_waitcnt vmcnt(0) lgkmcnt(0)
	s_barrier
	v_cmp_eq_u32_e32 vcc, 0, v0
	s_and_saveexec_b64 s[4:5], vcc
	s_cbranch_execz .Lgb5_done
	s_add_u32 s8, s88, 0xb20000
	s_addc_u32 s9, s89, 0
	v_mov_b32_e32 v10, 0
	v_mov_b32_e32 v11, 1
	s_lshl_b32 s0, s100, 8
	s_add_i32 s1, s0, 0x1000
	v_mov_b32_e32 v1, s1
	global_atomic_add v2, v1, v11, s[8:9] sc0
	s_add_i32 s2, s0, 0x2000
	s_mul_i32 s3, s98, 6
	s_mul_i32 s6, s99, 6
	s_waitcnt vmcnt(0)
	v_readfirstlane_b32 s7, v2
	s_add_i32 s7, s7, 1
	s_cmp_eq_u32 s7, s3
	s_cbranch_scc0 .Lgb5_wait
	buffer_wbl2 sc1
	s_waitcnt vmcnt(0)
	v_mov_b32_e32 v12, 0x2000
	global_atomic_add v12, v11, s[8:9]
	global_atomic_add v12, v11, s[8:9] offset:256
	global_atomic_add v12, v11, s[8:9] offset:512
	global_atomic_add v12, v11, s[8:9] offset:768
	global_atomic_add v12, v11, s[8:9] offset:1024
	global_atomic_add v12, v11, s[8:9] offset:1280
	global_atomic_add v12, v11, s[8:9] offset:1536
	global_atomic_add v12, v11, s[8:9] offset:1792

; #define RUN_PHASE(k, fn)                                  \
;   if (ph_lo <= k && k <= ph_hi) {                         \
;     if (k == PROBE_DUP) { fn(p, smem); cg::this_grid().sync(); } \
;     fn(p, smem);                                          \
;     if (k < ph_hi) cg::this_grid().sync();                \
;   }
; __global__ void __launch_bounds__(512) mega(Params p, int ph_lo, int ph_hi) {
;     ...
;   RUN_PHASE(7, phase7)
.LBB0_836:
	s_cmp_lt_i32 s91, 8
	s_cbranch_scc1 .LBB0_848
	s_waitcnt vmcnt(0) lgkmcnt(0)
	s_barrier
	v_cmp_eq_u32_e32 vcc, 0, v0
	s_and_saveexec_b64 s[4:5], vcc
	s_cbranch_execz .Lgb6_done
	s_add_u32 s8, s88, 0xb20000
	s_addc_u32 s9, s89, 0
	v_mov_b32_e32 v10, 0
	v_mov_b32_e32 v11, 1
	s_lshl_b32 s0, s100, 8
	s_add_i32 s1, s0, 0x1000
	v_mov_b32_e32 v1, s1
	global_atomic_add v2, v1, v11, s[8:9] sc0
	s_add_i32 s2, s0, 0x2000
	s_mul_i32 s3, s98, 7
	s_mul_i32 s6, s99, 7
	s_waitcnt vmcnt(0)
	v_readfirstlane_b32 s7, v2
	s_add_i32 s7, s7, 1
	s_cmp_eq_u32 s7, s3
	s_cbranch_scc0 .Lgb6_wait
	buffer_wbl2 sc1
	s_waitcnt vmcnt(0)
	v_mov_b32_e32 v12, 0x2000
	global_atomic_add v12, v11, s[8:9]
	global_atomic_add v12, v11, s[8:9] offset:256
	global_atomic_add v12, v11, s[8:9] offset:512
	global_atomic_add v12, v11, s[8:9] offset:768
	global_atomic_add v12, v11, s[8:9] offset:1024
	global_atomic_add v12, v11, s[8:9] offset:1280
	global_atomic_add v12, v11, s[8:9] offset:1536
	global_atomic_add v12, v11, s[8:9] offset:1792
